# accumulator zeroing in the P1/P4/P5/P7 tile headers with 64 v_mov_b64 instead of 128 v_mov_b32
# baseline (speedup 1.0000x reference)
; template <class Epi, class SchedT, bool ALIGN_EPI, bool SP2>
; __device__ __forceinline__ void gemm_phase(LAS unsigned char* lds, const int ldk, const int nt, const SchedT& S, const Epi& E) {
;     ...
;         for (int a = 0; a < 2; ++a)
; #pragma unroll
;             for (int b = 0; b < 2; ++b)
; #pragma unroll
;                 for (int m = 0; m < 4; ++m)
; #pragma unroll
;                     for (int n = 0; n < 2; ++n) acc[a][b][m][n] = (f32x4){0.f, 0.f, 0.f, 0.f};
;         }
;         cur = nxt; cA = nA; cB = nB; ++ui;
.LBB0_122:
	s_add_u32 s0, s12, 0x80080
	s_addc_u32 s1, s13, 0
	s_add_u32 s18, s16, 0x100
	v_mov_b64_e32 v[4:5], 0
	s_addc_u32 s19, s17, 0
	s_mov_b32 s21, -2
	v_mov_b64_e32 v[6:7], 0
	v_mov_b64_e32 v[8:9], 0
	v_mov_b64_e32 v[10:11], 0
	v_mov_b64_e32 v[20:21], 0
	v_mov_b64_e32 v[22:23], 0
	v_mov_b64_e32 v[24:25], 0
	v_mov_b64_e32 v[26:27], 0
	v_mov_b64_e32 v[36:37], 0
	v_mov_b64_e32 v[38:39], 0
	v_mov_b64_e32 v[40:41], 0
	v_mov_b64_e32 v[42:43], 0
	v_mov_b64_e32 v[52:53], 0
	v_mov_b64_e32 v[54:55], 0
	v_mov_b64_e32 v[56:57], 0
	v_mov_b64_e32 v[58:59], 0
	v_mov_b64_e32 v[12:13], 0
	v_mov_b64_e32 v[14:15], 0
	v_mov_b64_e32 v[16:17], 0
	v_mov_b64_e32 v[18:19], 0
	v_mov_b64_e32 v[28:29], 0
	v_mov_b64_e32 v[30:31], 0
	v_mov_b64_e32 v[32:33], 0
	v_mov_b64_e32 v[34:35], 0
	v_mov_b64_e32 v[44:45], 0
	v_mov_b64_e32 v[46:47], 0
	v_mov_b64_e32 v[48:49], 0
	v_mov_b64_e32 v[50:51], 0
	v_mov_b64_e32 v[60:61], 0
	v_mov_b64_e32 v[62:63], 0
	v_mov_b64_e32 v[64:65], 0
	v_mov_b64_e32 v[66:67], 0
	v_mov_b64_e32 v[68:69], 0
	v_mov_b64_e32 v[70:71], 0
	v_mov_b64_e32 v[72:73], 0
	v_mov_b64_e32 v[74:75], 0
	v_mov_b64_e32 v[84:85], 0
	v_mov_b64_e32 v[86:87], 0
	v_mov_b64_e32 v[88:89], 0
	v_mov_b64_e32 v[90:91], 0
	v_mov_b64_e32 v[100:101], 0
	v_mov_b64_e32 v[102:103], 0
	v_mov_b64_e32 v[104:105], 0
	v_mov_b64_e32 v[106:107], 0
	v_mov_b64_e32 v[116:117], 0
	v_mov_b64_e32 v[118:119], 0
	v_mov_b64_e32 v[120:121], 0
	v_mov_b64_e32 v[122:123], 0
	v_mov_b64_e32 v[76:77], 0
	v_mov_b64_e32 v[78:79], 0
	v_mov_b64_e32 v[80:81], 0
	v_mov_b64_e32 v[82:83], 0
	v_mov_b64_e32 v[92:93], 0
	v_mov_b64_e32 v[94:95], 0
	v_mov_b64_e32 v[96:97], 0
	v_mov_b64_e32 v[98:99], 0
	v_mov_b64_e32 v[108:109], 0
	v_mov_b64_e32 v[110:111], 0
	v_mov_b64_e32 v[112:113], 0
	v_mov_b64_e32 v[114:115], 0
	v_mov_b64_e32 v[124:125], 0
	v_mov_b64_e32 v[126:127], 0
	v_mov_b64_e32 v[128:129], 0
	v_mov_b64_e32 v[130:131], 0

; template <class Epi, class SchedT, bool ALIGN_EPI, bool SP2>
; __device__ __forceinline__ void gemm_phase(LAS unsigned char* lds, const int ldk, const int nt, const SchedT& S, const Epi& E) {
;     ...
;         for (int a = 0; a < 2; ++a)
; #pragma unroll
;             for (int b = 0; b < 2; ++b)
; #pragma unroll
;                 for (int m = 0; m < 4; ++m)
; #pragma unroll
;                     for (int n = 0; n < 2; ++n) acc[a][b][m][n] = (f32x4){0.f, 0.f, 0.f, 0.f};
;         }
;         cur = nxt; cA = nA; cB = nB; ++ui;
.LBB0_667:
	s_add_u32 s34, s34, 0x80080
	s_addc_u32 s35, s35, 0
	s_add_u32 s13, s36, 0x100
	v_mov_b64_e32 v[2:3], 0
	s_addc_u32 s20, s37, 0
	s_mov_b32 s22, -2
	s_waitcnt lgkmcnt(0)
	v_mov_b64_e32 v[4:5], 0
	v_mov_b64_e32 v[6:7], 0
	v_mov_b64_e32 v[8:9], 0
	v_mov_b64_e32 v[18:19], 0
	v_mov_b64_e32 v[20:21], 0
	v_mov_b64_e32 v[22:23], 0
	v_mov_b64_e32 v[24:25], 0
	v_mov_b64_e32 v[34:35], 0
	v_mov_b64_e32 v[36:37], 0
	v_mov_b64_e32 v[38:39], 0
	v_mov_b64_e32 v[40:41], 0
	v_mov_b64_e32 v[50:51], 0
	v_mov_b64_e32 v[52:53], 0
	v_mov_b64_e32 v[54:55], 0
	v_mov_b64_e32 v[56:57], 0
	v_mov_b64_e32 v[10:11], 0
	v_mov_b64_e32 v[12:13], 0
	v_mov_b64_e32 v[14:15], 0
	v_mov_b64_e32 v[16:17], 0
	v_mov_b64_e32 v[26:27], 0
	v_mov_b64_e32 v[28:29], 0
	v_mov_b64_e32 v[30:31], 0
	v_mov_b64_e32 v[32:33], 0
	v_mov_b64_e32 v[42:43], 0
	v_mov_b64_e32 v[44:45], 0
	v_mov_b64_e32 v[46:47], 0
	v_mov_b64_e32 v[48:49], 0
	v_mov_b64_e32 v[58:59], 0
	v_mov_b64_e32 v[60:61], 0
	v_mov_b64_e32 v[62:63], 0
	v_mov_b64_e32 v[64:65], 0
	v_mov_b64_e32 v[66:67], 0
	v_mov_b64_e32 v[68:69], 0
	v_mov_b64_e32 v[70:71], 0
	v_mov_b64_e32 v[72:73], 0
	v_mov_b64_e32 v[82:83], 0
	v_mov_b64_e32 v[84:85], 0
	v_mov_b64_e32 v[86:87], 0
	v_mov_b64_e32 v[88:89], 0
	v_mov_b64_e32 v[98:99], 0
	v_mov_b64_e32 v[100:101], 0
	v_mov_b64_e32 v[102:103], 0
	v_mov_b64_e32 v[104:105], 0
	v_mov_b64_e32 v[114:115], 0
	v_mov_b64_e32 v[116:117], 0
	v_mov_b64_e32 v[118:119], 0
	v_mov_b64_e32 v[120:121], 0
	v_mov_b64_e32 v[74:75], 0
	v_mov_b64_e32 v[76:77], 0
	v_mov_b64_e32 v[78:79], 0
	v_mov_b64_e32 v[80:81], 0
	v_mov_b64_e32 v[90:91], 0
	v_mov_b64_e32 v[92:93], 0
	v_mov_b64_e32 v[94:95], 0
	v_mov_b64_e32 v[96:97], 0
	v_mov_b64_e32 v[106:107], 0
	v_mov_b64_e32 v[108:109], 0
	v_mov_b64_e32 v[110:111], 0
	v_mov_b64_e32 v[112:113], 0
	v_mov_b64_e32 v[122:123], 0
	v_mov_b64_e32 v[124:125], 0
	v_mov_b64_e32 v[126:127], 0
	v_mov_b64_e32 v[128:129], 0

; template <class Epi, class SchedT, bool ALIGN_EPI, bool SP2>
; __device__ __forceinline__ void gemm_phase(LAS unsigned char* lds, const int ldk, const int nt, const SchedT& S, const Epi& E) {
;     ...
;         for (int a = 0; a < 2; ++a)
; #pragma unroll
;             for (int b = 0; b < 2; ++b)
; #pragma unroll
;                 for (int m = 0; m < 4; ++m)
; #pragma unroll
;                     for (int n = 0; n < 2; ++n) acc[a][b][m][n] = (f32x4){0.f, 0.f, 0.f, 0.f};
;         }
;         cur = nxt; cA = nA; cB = nB; ++ui;
.LBB0_751:
	s_add_u32 s34, s34, 0x80080
	s_addc_u32 s35, s35, 0
	s_add_u32 s13, s36, 0x100
	v_mov_b64_e32 v[2:3], 0
	s_addc_u32 s17, s37, 0
	s_mov_b32 s59, -2
	v_mov_b64_e32 v[4:5], 0
	v_mov_b64_e32 v[66:67], 0
	v_mov_b64_e32 v[68:69], 0
	v_mov_b64_e32 v[6:7], 0
	v_mov_b64_e32 v[8:9], 0
	v_mov_b64_e32 v[70:71], 0
	v_mov_b64_e32 v[72:73], 0
	v_mov_b64_e32 v[18:19], 0
	v_mov_b64_e32 v[20:21], 0
	v_mov_b64_e32 v[82:83], 0
	v_mov_b64_e32 v[84:85], 0
	v_mov_b64_e32 v[22:23], 0
	v_mov_b64_e32 v[24:25], 0
	v_mov_b64_e32 v[86:87], 0
	v_mov_b64_e32 v[88:89], 0
	v_mov_b64_e32 v[10:11], 0
	v_mov_b64_e32 v[12:13], 0
	v_mov_b64_e32 v[74:75], 0
	v_mov_b64_e32 v[76:77], 0
	v_mov_b64_e32 v[14:15], 0
	v_mov_b64_e32 v[16:17], 0
	v_mov_b64_e32 v[78:79], 0
	v_mov_b64_e32 v[80:81], 0
	v_mov_b64_e32 v[26:27], 0
	v_mov_b64_e32 v[28:29], 0
	v_mov_b64_e32 v[90:91], 0
	v_mov_b64_e32 v[92:93], 0
	v_mov_b64_e32 v[30:31], 0
	v_mov_b64_e32 v[32:33], 0
	v_mov_b64_e32 v[94:95], 0
	v_mov_b64_e32 v[96:97], 0
	v_mov_b64_e32 v[34:35], 0
	v_mov_b64_e32 v[36:37], 0
	v_mov_b64_e32 v[98:99], 0
	v_mov_b64_e32 v[100:101], 0
	v_mov_b64_e32 v[38:39], 0
	v_mov_b64_e32 v[40:41], 0
	v_mov_b64_e32 v[102:103], 0
	v_mov_b64_e32 v[104:105], 0
	v_mov_b64_e32 v[50:51], 0
	v_mov_b64_e32 v[52:53], 0
	v_mov_b64_e32 v[114:115], 0
	v_mov_b64_e32 v[116:117], 0
	v_mov_b64_e32 v[54:55], 0
	v_mov_b64_e32 v[56:57], 0
	v_mov_b64_e32 v[122:123], 0
	v_mov_b64_e32 v[124:125], 0
	v_mov_b64_e32 v[42:43], 0
	v_mov_b64_e32 v[44:45], 0
	v_mov_b64_e32 v[106:107], 0
	v_mov_b64_e32 v[108:109], 0
	v_mov_b64_e32 v[46:47], 0
	v_mov_b64_e32 v[48:49], 0
	v_mov_b64_e32 v[110:111], 0
	v_mov_b64_e32 v[112:113], 0
	v_mov_b64_e32 v[58:59], 0
	v_mov_b64_e32 v[60:61], 0
	v_mov_b64_e32 v[118:119], 0
	v_mov_b64_e32 v[120:121], 0
	v_mov_b64_e32 v[62:63], 0
	v_mov_b64_e32 v[64:65], 0
	v_mov_b64_e32 v[126:127], 0
	v_mov_b64_e32 v[128:129], 0

; template <class Epi, class SchedT, bool ALIGN_EPI, bool SP2>
; __device__ __forceinline__ void gemm_phase(LAS unsigned char* lds, const int ldk, const int nt, const SchedT& S, const Epi& E) {
;     ...
;         for (int a = 0; a < 2; ++a)
; #pragma unroll
;             for (int b = 0; b < 2; ++b)
; #pragma unroll
;                 for (int m = 0; m < 4; ++m)
; #pragma unroll
;                     for (int n = 0; n < 2; ++n) acc[a][b][m][n] = (f32x4){0.f, 0.f, 0.f, 0.f};
;         }
;         cur = nxt; cA = nA; cB = nB; ++ui;
.LBB0_947:
	s_add_u32 s81, s16, 0x100
	v_mov_b64_e32 v[2:3], 0
	s_addc_u32 s82, s17, 0
	s_mov_b32 s83, -2
	s_waitcnt lgkmcnt(0)
	v_mov_b64_e32 v[4:5], 0
	v_mov_b64_e32 v[6:7], 0
	v_mov_b64_e32 v[8:9], 0
	v_mov_b64_e32 v[18:19], 0
	v_mov_b64_e32 v[20:21], 0
	v_mov_b64_e32 v[22:23], 0
	v_mov_b64_e32 v[24:25], 0
	v_mov_b64_e32 v[34:35], 0
	v_mov_b64_e32 v[36:37], 0
	v_mov_b64_e32 v[38:39], 0
	v_mov_b64_e32 v[40:41], 0
	v_mov_b64_e32 v[50:51], 0
	v_mov_b64_e32 v[52:53], 0
	v_mov_b64_e32 v[54:55], 0
	v_mov_b64_e32 v[56:57], 0
	v_mov_b64_e32 v[10:11], 0
	v_mov_b64_e32 v[12:13], 0
	v_mov_b64_e32 v[14:15], 0
	v_mov_b64_e32 v[16:17], 0
	v_mov_b64_e32 v[26:27], 0
	v_mov_b64_e32 v[28:29], 0
	v_mov_b64_e32 v[30:31], 0
	v_mov_b64_e32 v[32:33], 0
	v_mov_b64_e32 v[42:43], 0
	v_mov_b64_e32 v[44:45], 0
	v_mov_b64_e32 v[46:47], 0
	v_mov_b64_e32 v[48:49], 0
	v_mov_b64_e32 v[58:59], 0
	v_mov_b64_e32 v[60:61], 0
	v_mov_b64_e32 v[62:63], 0
	v_mov_b64_e32 v[64:65], 0
	v_mov_b64_e32 v[66:67], 0
	v_mov_b64_e32 v[68:69], 0
	v_mov_b64_e32 v[70:71], 0
	v_mov_b64_e32 v[72:73], 0
	v_mov_b64_e32 v[82:83], 0
	v_mov_b64_e32 v[84:85], 0
	v_mov_b64_e32 v[86:87], 0
	v_mov_b64_e32 v[88:89], 0
	v_mov_b64_e32 v[98:99], 0
	v_mov_b64_e32 v[100:101], 0
	v_mov_b64_e32 v[102:103], 0
	v_mov_b64_e32 v[104:105], 0
	v_mov_b64_e32 v[114:115], 0
	v_mov_b64_e32 v[116:117], 0
	v_mov_b64_e32 v[118:119], 0
	v_mov_b64_e32 v[120:121], 0
	v_mov_b64_e32 v[74:75], 0
	v_mov_b64_e32 v[76:77], 0
	v_mov_b64_e32 v[78:79], 0
	v_mov_b64_e32 v[80:81], 0
	v_mov_b64_e32 v[90:91], 0
	v_mov_b64_e32 v[92:93], 0
	v_mov_b64_e32 v[94:95], 0
	v_mov_b64_e32 v[96:97], 0
	v_mov_b64_e32 v[106:107], 0
	v_mov_b64_e32 v[108:109], 0
	v_mov_b64_e32 v[110:111], 0
	v_mov_b64_e32 v[112:113], 0
	v_mov_b64_e32 v[122:123], 0
	v_mov_b64_e32 v[124:125], 0
	v_mov_b64_e32 v[126:127], 0
	v_mov_b64_e32 v[128:129], 0
